# attention: V and next-half K LDS reads issued in the mandatory wait-state bubble right after the QK MFMAs; the s_nop 7 pads replaced by those reads
# speedup vs baseline: 1.0019x; 1.0019x over previous
; #define LAS __attribute__((address_space(3)))
; #define MFMA32(a, b, c) __builtin_amdgcn_mfma_f32_32x32x16_bf16(a, b, c, 0, 0, 0)
; __device__ __forceinline__ void attn_unit(int bh, int qb, const bf16_t* QKV, const bf16_t* KF, const float* cstab, const float* qg, bf16_t* MIX, LAS unsigned char* lds) {
;     ...
;             const int key0 = 64 * t + 32 * kb;
;             if (key0 > qw + 31) continue;
;             const LAS unsigned char* kp = buf + (32 * kb + r32) * KROW + 16 * hi;
;             f32x16 p = negm;
;             bf16x8 kfr[6];
; #pragma unroll
;             for (int d0 = 0; d0 < 6; ++d0) kfr[d0] = *(const LAS bf16x8*)(kp + 32 * d0);
;             __builtin_amdgcn_s_setprio(1);
; #pragma unroll
;             for (int d0 = 0; d0 < 6; ++d0) p = MFMA32(kfr[d0], qf[d0], p);
;             __builtin_amdgcn_s_setprio(0);
;             if (key0 + 31 > qw) {
; #pragma unroll
;                 for (int r = 0; r < 16; ++r) { const int key = key0 + (r & 3) + 8 * (r >> 2) + 4 * hi; if (key > q) p[r] = -1e30f; }
.LBB0_1061:
	s_and_b32 s23, 1, s40
	s_cselect_b32 s22, 0, 0x6400
	s_add_i32 s44, s22, 0
	s_add_i32 s22, s43, 64
	v_add_u32_e32 v48, s44, v102
	v_add_u32_e32 v119, s44, v118
	s_cmp_gt_i32 s22, s2
	v_add_u32_e32 v120, v48, v114
	s_cbranch_scc1 .LBB0_1068
	ds_read_b128 v[122:125], v120
	ds_read_b128 v[126:129], v120 offset:32
	ds_read_b128 v[130:133], v120 offset:64
	ds_read_b128 v[140:143], v120 offset:96
	ds_read_b128 v[144:147], v120 offset:128
	ds_read_b128 v[148:151], v120 offset:160
	s_setprio 1
	s_waitcnt lgkmcnt(5)
	v_mfma_f32_32x32x16_bf16 v[48:63], v[122:125], v[74:77], v[32:47]
	s_waitcnt lgkmcnt(4)
	v_mfma_f32_32x32x16_bf16 v[48:63], v[126:129], v[78:81], v[48:63]
	s_waitcnt lgkmcnt(3)
	v_mfma_f32_32x32x16_bf16 v[48:63], v[130:133], v[82:85], v[48:63]
	s_waitcnt lgkmcnt(2)
	v_mfma_f32_32x32x16_bf16 v[48:63], v[140:143], v[90:93], v[48:63]
	s_waitcnt lgkmcnt(1)
	v_mfma_f32_32x32x16_bf16 v[48:63], v[144:147], v[94:97], v[48:63]
	s_waitcnt lgkmcnt(0)
	v_mfma_f32_32x32x16_bf16 v[48:63], v[148:151], v[98:101], v[48:63]
	v_add_u32_e32 v172, v119, v115
	ds_read_b64_tr_b16 v[156:157], v172 offset:13312
	ds_read_b64_tr_b16 v[158:159], v172 offset:14848
	ds_read_b64_tr_b16 v[160:161], v172 offset:16384
	ds_read_b64_tr_b16 v[162:163], v172 offset:17920
	ds_read_b64_tr_b16 v[164:165], v172 offset:13376
	ds_read_b64_tr_b16 v[166:167], v172 offset:14912
	ds_read_b64_tr_b16 v[168:169], v172 offset:16448
	ds_read_b64_tr_b16 v[170:171], v172 offset:17984
	ds_read_b128 v[202:205], v120 offset:6656
	ds_read_b128 v[206:209], v120 offset:6688
	ds_read_b128 v[210:213], v120 offset:6720
	ds_read_b128 v[214:217], v120 offset:6752
	ds_read_b128 v[218:221], v120 offset:6784
	ds_read_b128 v[222:225], v120 offset:6816
	s_setprio 0
	s_add_i32 s44, s43, 0x5f
	s_cmp_le_i32 s44, s37
	s_cbranch_scc1 .LBB0_1064
	v_add_u32_e32 v121, s43, v105
	v_add_u32_e32 v122, 64, v121
	v_cmp_lt_i32_e32 vcc, v122, v139
	s_nop 4
	v_cndmask_b32_e32 v49, v239, v49, vcc
	v_cmp_le_i32_e32 vcc, v122, v139
	v_add_u32_e32 v122, 0x42, v121
	s_nop 0
	v_cndmask_b32_e32 v48, v239, v48, vcc
	v_cmp_le_i32_e32 vcc, v122, v139
	v_add_u32_e32 v122, 0x43, v121
	s_nop 0
	v_cndmask_b32_e32 v50, v239, v50, vcc
	v_cmp_le_i32_e32 vcc, v122, v139
	v_add_u32_e32 v122, 0x48, v121
	s_nop 0
	v_cndmask_b32_e32 v51, v239, v51, vcc
	v_cmp_le_i32_e32 vcc, v122, v139
	v_add_u32_e32 v122, 0x49, v121
	s_nop 0
	v_cndmask_b32_e32 v52, v239, v52, vcc
	v_cmp_le_i32_e32 vcc, v122, v139
	v_add_u32_e32 v122, 0x4a, v121
	s_nop 0
	v_cndmask_b32_e32 v53, v239, v53, vcc
	v_cmp_le_i32_e32 vcc, v122, v139
	v_add_u32_e32 v122, 0x4b, v121
	s_nop 0
	v_cndmask_b32_e32 v54, v239, v54, vcc
	v_cmp_le_i32_e32 vcc, v122, v139
	v_add_u32_e32 v122, 0x50, v121
	s_nop 0
	v_cndmask_b32_e32 v55, v239, v55, vcc
	v_cmp_le_i32_e32 vcc, v122, v139
	v_add_u32_e32 v122, 0x51, v121
	s_nop 0
	v_cndmask_b32_e32 v56, v239, v56, vcc
	v_cmp_le_i32_e32 vcc, v122, v139
	v_add_u32_e32 v122, 0x52, v121
	s_nop 0
	v_cndmask_b32_e32 v57, v239, v57, vcc
	v_cmp_le_i32_e32 vcc, v122, v139
	v_add_u32_e32 v122, 0x53, v121
	s_nop 0
	v_cndmask_b32_e32 v58, v239, v58, vcc
	v_cmp_le_i32_e32 vcc, v122, v139
	v_add_u32_e32 v122, 0x58, v121
	s_nop 0
	v_cndmask_b32_e32 v59, v239, v59, vcc
	v_cmp_le_i32_e32 vcc, v122, v139
	v_add_u32_e32 v122, 0x59, v121
	s_nop 0
	v_cndmask_b32_e32 v60, v239, v60, vcc
	v_cmp_le_i32_e32 vcc, v122, v139
	v_add_u32_e32 v122, 0x5a, v121
	v_add_u32_e32 v121, 0x5b, v121
	v_cndmask_b32_e32 v61, v239, v61, vcc
	v_cmp_le_i32_e32 vcc, v122, v139
	s_nop 1
	v_cndmask_b32_e32 v62, v239, v62, vcc
	v_cmp_le_i32_e32 vcc, v121, v139
	s_nop 1
	v_cndmask_b32_e32 v63, v239, v63, vcc
; #define LAS __attribute__((address_space(3)))
; #define MFMA32(a, b, c) __builtin_amdgcn_mfma_f32_32x32x16_bf16(a, b, c, 0, 0, 0)
; __device__ __forceinline__ void attn_unit(int bh, int qb, const bf16_t* QKV, const bf16_t* KF, const float* cstab, const float* qg, bf16_t* MIX, LAS unsigned char* lds) {
;     ...
;             float mx = fmaxf(fmaxf(p[0], p[1]), fmaxf(p[2], p[3]));
; #pragma unroll
;             for (int r = 4; r < 16; r += 4) mx = fmaxf(mx, fmaxf(fmaxf(p[r], p[r + 1]), fmaxf(p[r + 2], p[r + 3])));
;             mx = pg8::max32(mx);
;             if (key0 == 0 || __any(mx > 4.0f)) {
;                 const float dl = (key0 == 0) ? mx : fmaxf(mx, 0.f), f = __builtin_amdgcn_exp2f(-dl);
;                 mrun += dl; lrun *= f;
; #pragma unroll
;                 for (int r = 0; r < 16; ++r) { o0[r] *= f; o1[r] *= f; p[r] -= dl; negm[r] = -mrun; }
;             }
;             float ps = 0.f;
; #pragma unroll
;             for (int r = 0; r < 16; ++r) { p[r] = __builtin_amdgcn_exp2f(p[r]); ps += p[r]; }
;             lrun += ps;
;             u32x4 w0, w1;
; #pragma unroll
;             for (int k = 0; k < 4; ++k) { w0[k] = cvt_pk_bf16(p[2 * k], p[2 * k + 1]); w1[k] = cvt_pk_bf16(p[8 + 2 * k], p[8 + 2 * k + 1]); }
;             const bf16x8 pb0 = __builtin_bit_cast(bf16x8, w0), pb1 = __builtin_bit_cast(bf16x8, w1);
;             const LAS unsigned char* vp = buf + vtb + (32 * kb) * VROW;
; #pragma unroll
;             for (int db = 0; db < 2; ++db) {
;                 const v4i16_t a0 = __builtin_amdgcn_ds_read_tr16_b64_v4i16((LAS v4i16_t*)(vp + db * 64));
;                 const v4i16_t a1 = __builtin_amdgcn_ds_read_tr16_b64_v4i16((LAS v4i16_t*)(vp + db * 64 + 8 * VROW));
;                 const v4i16_t c0 = __builtin_amdgcn_ds_read_tr16_b64_v4i16((LAS v4i16_t*)(vp + db * 64 + 16 * VROW));
;                 const v4i16_t c1 = __builtin_amdgcn_ds_read_tr16_b64_v4i16((LAS v4i16_t*)(vp + db * 64 + 24 * VROW));
;                 const bf16x8 va = {a0[0], a0[1], a0[2], a0[3], a1[0], a1[1], a1[2], a1[3]}, vc = {c0[0], c0[1], c0[2], c0[3], c1[0], c1[1], c1[2], c1[3]};
;                 __builtin_amdgcn_s_setprio(1);
;                 if (db == 0) { o0 = MFMA32(va, pb0, o0); o0 = MFMA32(vc, pb1, o0); }
;                 else { o1 = MFMA32(va, pb0, o1); o1 = MFMA32(vc, pb1, o1); }
;                 __builtin_amdgcn_s_setprio(0);
;             }
.LBB0_1064:
	s_nop 0
	v_max3_f32 v121, v48, v49, v50
	v_max3_f32 v122, v51, v52, v53
	v_max3_f32 v123, v54, v55, v56
	v_max3_f32 v124, v57, v58, v59
	v_max3_f32 v121, v121, v122, v123
	v_max3_f32 v122, v60, v61, v62
	v_max3_f32 v121, v121, v124, v122
	v_max_f32_e32 v121, v121, v63
	v_cmp_lt_f32_e32 vcc, 4.0, v121
	s_cbranch_vccz .LBB0_1066
	v_mov_b32_e32 v122, v121
	s_nop 1
	v_permlane32_swap_b32_e32 v121, v122
	v_max_f32_e32 v121, v121, v122
	v_max_f32_e32 v32, v121, v121
	v_max_f32_e32 v34, 0, v32
	v_exp_f32_e64 v122, -v34
	v_add_f32_e32 v106, v106, v34
	v_xor_b32_e32 v32, 0x80000000, v106
	v_pk_add_f32 v[48:49], v[48:49], v[34:35] op_sel_hi:[1,0] neg_lo:[0,1] neg_hi:[0,1]
	v_pk_add_f32 v[50:51], v[50:51], v[34:35] op_sel_hi:[1,0] neg_lo:[0,1] neg_hi:[0,1]
	v_pk_add_f32 v[52:53], v[52:53], v[34:35] op_sel_hi:[1,0] neg_lo:[0,1] neg_hi:[0,1]
	v_pk_add_f32 v[54:55], v[54:55], v[34:35] op_sel_hi:[1,0] neg_lo:[0,1] neg_hi:[0,1]
	v_pk_add_f32 v[56:57], v[56:57], v[34:35] op_sel_hi:[1,0] neg_lo:[0,1] neg_hi:[0,1]
	v_pk_add_f32 v[58:59], v[58:59], v[34:35] op_sel_hi:[1,0] neg_lo:[0,1] neg_hi:[0,1]
	v_pk_add_f32 v[60:61], v[60:61], v[34:35] op_sel_hi:[1,0] neg_lo:[0,1] neg_hi:[0,1]
	v_pk_mul_f32 v[14:15], v[14:15], v[122:123] op_sel_hi:[1,0]
	v_pk_mul_f32 v[12:13], v[12:13], v[122:123] op_sel_hi:[1,0]
	v_pk_mul_f32 v[10:11], v[10:11], v[122:123] op_sel_hi:[1,0]
	v_pk_mul_f32 v[8:9], v[8:9], v[122:123] op_sel_hi:[1,0]
	v_pk_mul_f32 v[6:7], v[6:7], v[122:123] op_sel_hi:[1,0]
	v_pk_mul_f32 v[4:5], v[4:5], v[122:123] op_sel_hi:[1,0]
	v_pk_mul_f32 v[2:3], v[2:3], v[122:123] op_sel_hi:[1,0]
	v_pk_mul_f32 v[0:1], v[0:1], v[122:123] op_sel_hi:[1,0]
	v_pk_mul_f32 v[30:31], v[30:31], v[122:123] op_sel_hi:[1,0]
	v_pk_mul_f32 v[28:29], v[28:29], v[122:123] op_sel_hi:[1,0]
	v_pk_mul_f32 v[26:27], v[26:27], v[122:123] op_sel_hi:[1,0]
	v_pk_mul_f32 v[24:25], v[24:25], v[122:123] op_sel_hi:[1,0]
	v_pk_mul_f32 v[22:23], v[22:23], v[122:123] op_sel_hi:[1,0]
	v_pk_mul_f32 v[20:21], v[20:21], v[122:123] op_sel_hi:[1,0]
	v_pk_mul_f32 v[18:19], v[18:19], v[122:123] op_sel_hi:[1,0]
	v_pk_mul_f32 v[16:17], v[16:17], v[122:123] op_sel_hi:[1,0]
	v_pk_add_f32 v[62:63], v[62:63], v[34:35] op_sel_hi:[1,0] neg_lo:[0,1] neg_hi:[0,1]
	v_mov_b32_e32 v33, v32
	v_mov_b32_e32 v34, v32
	v_mov_b32_e32 v35, v32
	v_mov_b32_e32 v36, v32
	v_mov_b32_e32 v37, v32
	v_mov_b32_e32 v38, v32
	v_mov_b32_e32 v39, v32
	v_mov_b32_e32 v40, v32
	v_mov_b32_e32 v41, v32
	v_mov_b32_e32 v42, v32
	v_mov_b32_e32 v43, v32
	v_mov_b32_e32 v44, v32
	v_mov_b32_e32 v45, v32
	v_mov_b32_e32 v46, v32
	v_mov_b32_e32 v47, v32
	v_mul_f32_e32 v107, v107, v122
.LBB0_1066:
	v_exp_f32_e32 v48, v48
	v_exp_f32_e32 v49, v49
	v_exp_f32_e32 v50, v50
	v_exp_f32_e32 v51, v51
	v_exp_f32_e32 v122, v52
	v_add_f32_e32 v121, v49, v48
	v_add_f32_e32 v121, v50, v121
	v_add_f32_e32 v121, v51, v121
	v_add_f32_e32 v52, v122, v121
	v_exp_f32_e32 v121, v53
	v_exp_f32_e32 v123, v54
	v_exp_f32_e32 v55, v55
	v_exp_f32_e32 v53, v56
	v_add_f32_e32 v52, v121, v52
	v_exp_f32_e32 v54, v57
	v_add_f32_e32 v52, v123, v52
	v_exp_f32_e32 v56, v58
	v_add_f32_e32 v52, v55, v52
	v_exp_f32_e32 v57, v59
	v_add_f32_e32 v52, v53, v52
	v_exp_f32_e32 v58, v60
	v_add_f32_e32 v52, v54, v52
	v_exp_f32_e32 v59, v61
	v_add_f32_e32 v52, v56, v52
	v_exp_f32_e32 v60, v62
	v_add_f32_e32 v52, v57, v52
	v_exp_f32_e32 v61, v63
	v_add_f32_e32 v52, v58, v52
	v_add_f32_e32 v52, v59, v52
	v_add_f32_e32 v52, v60, v52
	v_cvt_pk_bf16_f32 v48, v48, v49
	v_cvt_pk_bf16_f32 v49, v50, v51
	v_cvt_pk_bf16_f32 v50, v122, v121
	v_add_f32_e32 v124, v61, v52
	v_cvt_pk_bf16_f32 v52, v53, v54
	v_cvt_pk_bf16_f32 v53, v56, v57
	v_cvt_pk_bf16_f32 v54, v58, v59
	v_cvt_pk_bf16_f32 v51, v123, v55
	v_cvt_pk_bf16_f32 v55, v60, v61
	s_setprio 1
	s_waitcnt lgkmcnt(12)
	v_mfma_f32_32x32x16_bf16 v[0:15], v[156:159], v[48:51], v[0:15]
	s_waitcnt lgkmcnt(10)
	v_mfma_f32_32x32x16_bf16 v[0:15], v[160:163], v[52:55], v[0:15]
	s_setprio 0
	s_setprio 1
	s_waitcnt lgkmcnt(8)
	v_mfma_f32_32x32x16_bf16 v[16:31], v[164:167], v[48:51], v[16:31]
	s_waitcnt lgkmcnt(6)
	v_mfma_f32_32x32x16_bf16 v[16:31], v[168:171], v[52:55], v[16:31]
	s_setprio 0
	v_add_f32_e32 v107, v107, v124
	s_add_i32 s44, s43, 0x60
	s_cmp_gt_i32 s44, s2
	s_cbranch_scc0 .LBB0_1069

; #define LAS __attribute__((address_space(3)))
; #define MFMA32(a, b, c) __builtin_amdgcn_mfma_f32_32x32x16_bf16(a, b, c, 0, 0, 0)
; __device__ __forceinline__ void attn_unit(int bh, int qb, const bf16_t* QKV, const bf16_t* KF, const float* cstab, const float* qg, bf16_t* MIX, LAS unsigned char* lds) {
;     ...
;             if (key0 > qw + 31) continue;
;             const LAS unsigned char* kp = buf + (32 * kb + r32) * KROW + 16 * hi;
;             f32x16 p = negm;
;             bf16x8 kfr[6];
; #pragma unroll
;             for (int d0 = 0; d0 < 6; ++d0) kfr[d0] = *(const LAS bf16x8*)(kp + 32 * d0);
;             __builtin_amdgcn_s_setprio(1);
; #pragma unroll
;             for (int d0 = 0; d0 < 6; ++d0) p = MFMA32(kfr[d0], qf[d0], p);
;             __builtin_amdgcn_s_setprio(0);
;             if (key0 + 31 > qw) {
; #pragma unroll
;                 for (int r = 0; r < 16; ++r) { const int key = key0 + (r & 3) + 8 * (r >> 2) + 4 * hi; if (key > q) p[r] = -1e30f; }
;     ...
;             const LAS unsigned char* vp = buf + vtb + (32 * kb) * VROW;
; #pragma unroll
;             for (int db = 0; db < 2; ++db) {
;                 const v4i16_t a0 = __builtin_amdgcn_ds_read_tr16_b64_v4i16((LAS v4i16_t*)(vp + db * 64));
;                 const v4i16_t a1 = __builtin_amdgcn_ds_read_tr16_b64_v4i16((LAS v4i16_t*)(vp + db * 64 + 8 * VROW));
;                 const v4i16_t c0 = __builtin_amdgcn_ds_read_tr16_b64_v4i16((LAS v4i16_t*)(vp + db * 64 + 16 * VROW));
;                 const v4i16_t c1 = __builtin_amdgcn_ds_read_tr16_b64_v4i16((LAS v4i16_t*)(vp + db * 64 + 24 * VROW));
.LBB0_1069:
	s_setprio 1
	s_waitcnt lgkmcnt(5)
	v_mfma_f32_32x32x16_bf16 v[48:63], v[202:205], v[74:77], v[32:47]
	s_waitcnt lgkmcnt(4)
	v_mfma_f32_32x32x16_bf16 v[48:63], v[206:209], v[78:81], v[48:63]
	s_waitcnt lgkmcnt(3)
	v_mfma_f32_32x32x16_bf16 v[48:63], v[210:213], v[82:85], v[48:63]
	s_waitcnt lgkmcnt(2)
	v_mfma_f32_32x32x16_bf16 v[48:63], v[214:217], v[90:93], v[48:63]
	s_waitcnt lgkmcnt(1)
	v_mfma_f32_32x32x16_bf16 v[48:63], v[218:221], v[94:97], v[48:63]
	s_waitcnt lgkmcnt(0)
	v_mfma_f32_32x32x16_bf16 v[48:63], v[222:225], v[98:101], v[48:63]
	v_add_u32_e32 v172, v119, v115
	ds_read_b64_tr_b16 v[156:157], v172 offset:19456
	ds_read_b64_tr_b16 v[158:159], v172 offset:20992
	ds_read_b64_tr_b16 v[160:161], v172 offset:22528
	ds_read_b64_tr_b16 v[162:163], v172 offset:24064
	ds_read_b64_tr_b16 v[164:165], v172 offset:19520
	ds_read_b64_tr_b16 v[166:167], v172 offset:21056
	ds_read_b64_tr_b16 v[168:169], v172 offset:22592
	ds_read_b64_tr_b16 v[170:171], v172 offset:24128
	s_setprio 0
	s_add_i32 s44, s43, 0x7f
	s_cmp_le_i32 s44, s37
	s_cbranch_scc1 .LBB0_1071
	v_add_u32_e32 v120, s43, v105
	v_add_u32_e32 v121, 0x60, v120
	v_cmp_lt_i32_e32 vcc, v121, v139
	s_nop 4
	v_cndmask_b32_e32 v49, v239, v49, vcc
	v_cmp_le_i32_e32 vcc, v121, v139
	v_add_u32_e32 v121, 0x62, v120
	s_nop 0
	v_cndmask_b32_e32 v48, v239, v48, vcc
	v_cmp_le_i32_e32 vcc, v121, v139
	v_add_u32_e32 v121, 0x63, v120
	s_nop 0
	v_cndmask_b32_e32 v50, v239, v50, vcc
	v_cmp_le_i32_e32 vcc, v121, v139
	v_add_u32_e32 v121, 0x68, v120
	s_nop 0
	v_cndmask_b32_e32 v51, v239, v51, vcc
	v_cmp_le_i32_e32 vcc, v121, v139
	v_add_u32_e32 v121, 0x69, v120
	s_nop 0
	v_cndmask_b32_e32 v52, v239, v52, vcc
	v_cmp_le_i32_e32 vcc, v121, v139
	v_add_u32_e32 v121, 0x6a, v120
	s_nop 0
	v_cndmask_b32_e32 v53, v239, v53, vcc
	v_cmp_le_i32_e32 vcc, v121, v139
	v_add_u32_e32 v121, 0x6b, v120
	s_nop 0
	v_cndmask_b32_e32 v54, v239, v54, vcc
	v_cmp_le_i32_e32 vcc, v121, v139
	v_add_u32_e32 v121, 0x70, v120
	s_nop 0
	v_cndmask_b32_e32 v55, v239, v55, vcc
	v_cmp_le_i32_e32 vcc, v121, v139
	v_add_u32_e32 v121, 0x71, v120
	s_nop 0
	v_cndmask_b32_e32 v56, v239, v56, vcc
	v_cmp_le_i32_e32 vcc, v121, v139
	v_add_u32_e32 v121, 0x72, v120
	s_nop 0
	v_cndmask_b32_e32 v57, v239, v57, vcc
	v_cmp_le_i32_e32 vcc, v121, v139
	v_add_u32_e32 v121, 0x73, v120
	s_nop 0
	v_cndmask_b32_e32 v58, v239, v58, vcc
	v_cmp_le_i32_e32 vcc, v121, v139
	v_add_u32_e32 v121, 0x78, v120
	s_nop 0
	v_cndmask_b32_e32 v59, v239, v59, vcc
	v_cmp_le_i32_e32 vcc, v121, v139
	v_add_u32_e32 v121, 0x79, v120
	s_nop 0
	v_cndmask_b32_e32 v60, v239, v60, vcc
	v_cmp_le_i32_e32 vcc, v121, v139
	v_add_u32_e32 v121, 0x7a, v120
	v_add_u32_e32 v120, 0x7b, v120
	v_cndmask_b32_e32 v61, v239, v61, vcc
	v_cmp_le_i32_e32 vcc, v121, v139
	s_nop 1
	v_cndmask_b32_e32 v62, v239, v62, vcc
	v_cmp_le_i32_e32 vcc, v120, v139
	s_nop 1
	v_cndmask_b32_e32 v63, v239, v63, vcc
; #define LAS __attribute__((address_space(3)))
; #define MFMA32(a, b, c) __builtin_amdgcn_mfma_f32_32x32x16_bf16(a, b, c, 0, 0, 0)
; __device__ __forceinline__ void attn_unit(int bh, int qb, const bf16_t* QKV, const bf16_t* KF, const float* cstab, const float* qg, bf16_t* MIX, LAS unsigned char* lds) {
;     ...
;             float mx = fmaxf(fmaxf(p[0], p[1]), fmaxf(p[2], p[3]));
; #pragma unroll
;             for (int r = 4; r < 16; r += 4) mx = fmaxf(mx, fmaxf(fmaxf(p[r], p[r + 1]), fmaxf(p[r + 2], p[r + 3])));
;             mx = pg8::max32(mx);
;             if (key0 == 0 || __any(mx > 4.0f)) {
;                 const float dl = (key0 == 0) ? mx : fmaxf(mx, 0.f), f = __builtin_amdgcn_exp2f(-dl);
;                 mrun += dl; lrun *= f;
; #pragma unroll
;                 for (int r = 0; r < 16; ++r) { o0[r] *= f; o1[r] *= f; p[r] -= dl; negm[r] = -mrun; }
;             }
;             float ps = 0.f;
; #pragma unroll
;             for (int r = 0; r < 16; ++r) { p[r] = __builtin_amdgcn_exp2f(p[r]); ps += p[r]; }
;             lrun += ps;
;             u32x4 w0, w1;
; #pragma unroll
;             for (int k = 0; k < 4; ++k) { w0[k] = cvt_pk_bf16(p[2 * k], p[2 * k + 1]); w1[k] = cvt_pk_bf16(p[8 + 2 * k], p[8 + 2 * k + 1]); }
;             const bf16x8 pb0 = __builtin_bit_cast(bf16x8, w0), pb1 = __builtin_bit_cast(bf16x8, w1);
;             const LAS unsigned char* vp = buf + vtb + (32 * kb) * VROW;
; #pragma unroll
;             for (int db = 0; db < 2; ++db) {
;                 const v4i16_t a0 = __builtin_amdgcn_ds_read_tr16_b64_v4i16((LAS v4i16_t*)(vp + db * 64));
;                 const v4i16_t a1 = __builtin_amdgcn_ds_read_tr16_b64_v4i16((LAS v4i16_t*)(vp + db * 64 + 8 * VROW));
;                 const v4i16_t c0 = __builtin_amdgcn_ds_read_tr16_b64_v4i16((LAS v4i16_t*)(vp + db * 64 + 16 * VROW));
;                 const v4i16_t c1 = __builtin_amdgcn_ds_read_tr16_b64_v4i16((LAS v4i16_t*)(vp + db * 64 + 24 * VROW));
;                 const bf16x8 va = {a0[0], a0[1], a0[2], a0[3], a1[0], a1[1], a1[2], a1[3]}, vc = {c0[0], c0[1], c0[2], c0[3], c1[0], c1[1], c1[2], c1[3]};
;                 __builtin_amdgcn_s_setprio(1);
;                 if (db == 0) { o0 = MFMA32(va, pb0, o0); o0 = MFMA32(vc, pb1, o0); }
;                 else { o1 = MFMA32(va, pb0, o1); o1 = MFMA32(vc, pb1, o1); }
;                 __builtin_amdgcn_s_setprio(0);
;             }
.LBB0_1071:
	s_nop 1
	v_max3_f32 v120, v48, v49, v50
	v_max3_f32 v121, v51, v52, v53
	v_max3_f32 v122, v54, v55, v56
	v_max3_f32 v123, v57, v58, v59
	v_max3_f32 v120, v120, v121, v122
	v_max3_f32 v121, v60, v61, v62
	v_max3_f32 v120, v120, v123, v121
	v_max_f32_e32 v120, v120, v63
	v_cmp_lt_f32_e32 vcc, 4.0, v120
	s_cbranch_vccz .LBB0_1073
	v_mov_b32_e32 v121, v120
	s_nop 1
	v_permlane32_swap_b32_e32 v120, v121
	v_max_f32_e32 v120, v120, v121
	v_max_f32_e32 v32, v120, v120
	v_max_f32_e32 v34, 0, v32
	v_exp_f32_e64 v120, -v34
	v_add_f32_e32 v106, v106, v34
	v_xor_b32_e32 v32, 0x80000000, v106
	v_pk_add_f32 v[48:49], v[48:49], v[34:35] op_sel_hi:[1,0] neg_lo:[0,1] neg_hi:[0,1]
	v_pk_add_f32 v[50:51], v[50:51], v[34:35] op_sel_hi:[1,0] neg_lo:[0,1] neg_hi:[0,1]
	v_pk_add_f32 v[52:53], v[52:53], v[34:35] op_sel_hi:[1,0] neg_lo:[0,1] neg_hi:[0,1]
	v_pk_add_f32 v[54:55], v[54:55], v[34:35] op_sel_hi:[1,0] neg_lo:[0,1] neg_hi:[0,1]
	v_pk_add_f32 v[56:57], v[56:57], v[34:35] op_sel_hi:[1,0] neg_lo:[0,1] neg_hi:[0,1]
	v_pk_add_f32 v[58:59], v[58:59], v[34:35] op_sel_hi:[1,0] neg_lo:[0,1] neg_hi:[0,1]
	v_pk_add_f32 v[60:61], v[60:61], v[34:35] op_sel_hi:[1,0] neg_lo:[0,1] neg_hi:[0,1]
	v_pk_mul_f32 v[14:15], v[14:15], v[120:121] op_sel_hi:[1,0]
	v_pk_mul_f32 v[12:13], v[12:13], v[120:121] op_sel_hi:[1,0]
	v_pk_mul_f32 v[10:11], v[10:11], v[120:121] op_sel_hi:[1,0]
	v_pk_mul_f32 v[8:9], v[8:9], v[120:121] op_sel_hi:[1,0]
	v_pk_mul_f32 v[6:7], v[6:7], v[120:121] op_sel_hi:[1,0]
	v_pk_mul_f32 v[4:5], v[4:5], v[120:121] op_sel_hi:[1,0]
	v_pk_mul_f32 v[2:3], v[2:3], v[120:121] op_sel_hi:[1,0]
	v_pk_mul_f32 v[0:1], v[0:1], v[120:121] op_sel_hi:[1,0]
	v_pk_mul_f32 v[30:31], v[30:31], v[120:121] op_sel_hi:[1,0]
	v_pk_mul_f32 v[28:29], v[28:29], v[120:121] op_sel_hi:[1,0]
	v_pk_mul_f32 v[26:27], v[26:27], v[120:121] op_sel_hi:[1,0]
	v_pk_mul_f32 v[24:25], v[24:25], v[120:121] op_sel_hi:[1,0]
	v_pk_mul_f32 v[22:23], v[22:23], v[120:121] op_sel_hi:[1,0]
	v_pk_mul_f32 v[20:21], v[20:21], v[120:121] op_sel_hi:[1,0]
	v_pk_mul_f32 v[18:19], v[18:19], v[120:121] op_sel_hi:[1,0]
	v_pk_mul_f32 v[16:17], v[16:17], v[120:121] op_sel_hi:[1,0]
	v_pk_add_f32 v[62:63], v[62:63], v[34:35] op_sel_hi:[1,0] neg_lo:[0,1] neg_hi:[0,1]
	v_mov_b32_e32 v33, v32
	v_mov_b32_e32 v34, v32
	v_mov_b32_e32 v35, v32
	v_mov_b32_e32 v36, v32
	v_mov_b32_e32 v37, v32
	v_mov_b32_e32 v38, v32
	v_mov_b32_e32 v39, v32
	v_mov_b32_e32 v40, v32
	v_mov_b32_e32 v41, v32
	v_mov_b32_e32 v42, v32
	v_mov_b32_e32 v43, v32
	v_mov_b32_e32 v44, v32
	v_mov_b32_e32 v45, v32
	v_mov_b32_e32 v46, v32
	v_mov_b32_e32 v47, v32
	v_mul_f32_e32 v107, v107, v120
.LBB0_1073:
	v_exp_f32_e32 v48, v48
	v_exp_f32_e32 v49, v49
	v_exp_f32_e32 v50, v50
	v_exp_f32_e32 v51, v51
	v_exp_f32_e32 v121, v52
	v_add_f32_e32 v120, v49, v48
	v_add_f32_e32 v120, v50, v120
	v_add_f32_e32 v120, v51, v120
	v_add_f32_e32 v52, v121, v120
	v_exp_f32_e32 v120, v53
	v_exp_f32_e32 v122, v54
	v_exp_f32_e32 v55, v55
	v_exp_f32_e32 v53, v56
	v_add_f32_e32 v52, v120, v52
	v_exp_f32_e32 v54, v57
	v_add_f32_e32 v52, v122, v52
	v_exp_f32_e32 v56, v58
	v_add_f32_e32 v52, v55, v52
	v_exp_f32_e32 v57, v59
	v_add_f32_e32 v52, v53, v52
	v_exp_f32_e32 v58, v60
	v_add_f32_e32 v52, v54, v52
	v_exp_f32_e32 v59, v61
	v_add_f32_e32 v52, v56, v52
	v_exp_f32_e32 v60, v62
	v_add_f32_e32 v52, v57, v52
	v_exp_f32_e32 v61, v63
	v_add_f32_e32 v52, v58, v52
	v_add_f32_e32 v52, v59, v52
	v_add_f32_e32 v52, v60, v52
	v_add_f32_e32 v123, v61, v52
	v_cvt_pk_bf16_f32 v48, v48, v49
	v_cvt_pk_bf16_f32 v52, v53, v54
	v_cvt_pk_bf16_f32 v49, v50, v51
	v_cvt_pk_bf16_f32 v53, v56, v57
	v_cvt_pk_bf16_f32 v54, v58, v59
	v_cvt_pk_bf16_f32 v51, v122, v55
	v_cvt_pk_bf16_f32 v55, v60, v61
	v_cvt_pk_bf16_f32 v50, v121, v120
	s_setprio 1
	s_waitcnt lgkmcnt(6)
	v_mfma_f32_32x32x16_bf16 v[0:15], v[156:159], v[48:51], v[0:15]
	s_waitcnt lgkmcnt(4)
	v_mfma_f32_32x32x16_bf16 v[0:15], v[160:163], v[52:55], v[0:15]
	s_setprio 0
	s_setprio 1
	s_waitcnt lgkmcnt(2)
	v_mfma_f32_32x32x16_bf16 v[16:31], v[164:167], v[48:51], v[16:31]
	s_waitcnt lgkmcnt(0)
	v_mfma_f32_32x32x16_bf16 v[16:31], v[168:171], v[52:55], v[16:31]
	s_setprio 0
	v_add_f32_e32 v107, v107, v123
	s_andn2_b64 vcc, exec, s[4:5]
	s_cbranch_vccnz .LBB0_1077

; #define LAS __attribute__((address_space(3)))
; #define MFMA32(a, b, c) __builtin_amdgcn_mfma_f32_32x32x16_bf16(a, b, c, 0, 0, 0)
; __device__ __forceinline__ void attn_unit(int bh, int qb, const bf16_t* QKV, const bf16_t* KF, const float* cstab, const float* qg, bf16_t* MIX, LAS unsigned char* lds) {
;     ...
;             const int key0 = 64 * t + 32 * kb;
;             if (key0 > qw + 31) continue;
;             const LAS unsigned char* kp = buf + (32 * kb + r32) * KROW + 16 * hi;
;             f32x16 p = negm;
;             bf16x8 kfr[6];
; #pragma unroll
;             for (int d0 = 0; d0 < 6; ++d0) kfr[d0] = *(const LAS bf16x8*)(kp + 32 * d0);
;             __builtin_amdgcn_s_setprio(1);
; #pragma unroll
;             for (int d0 = 0; d0 < 6; ++d0) p = MFMA32(kfr[d0], qf[d0], p);
;             __builtin_amdgcn_s_setprio(0);
;             if (key0 + 31 > qw) {
; #pragma unroll
;                 for (int r = 0; r < 16; ++r) { const int key = key0 + (r & 3) + 8 * (r >> 2) + 4 * hi; if (key > q) p[r] = -1e30f; }
.LBB0_1102:
	s_and_b32 s15, 1, s19
	s_cselect_b32 s14, 0, 0x6400
	s_add_i32 s30, s14, 0
	s_add_i32 s14, s29, 64
	v_add_u32_e32 v48, s30, v102
	v_add_u32_e32 v119, s30, v118
	s_cmp_gt_i32 s14, s18
	v_add_u32_e32 v120, v48, v114
	s_cbranch_scc1 .LBB0_1109
	ds_read_b128 v[122:125], v120
	ds_read_b128 v[126:129], v120 offset:32
	ds_read_b128 v[130:133], v120 offset:64
	ds_read_b128 v[140:143], v120 offset:96
	ds_read_b128 v[144:147], v120 offset:128
	ds_read_b128 v[148:151], v120 offset:160
	s_setprio 1
	s_waitcnt lgkmcnt(5)
	v_mfma_f32_32x32x16_bf16 v[48:63], v[122:125], v[74:77], v[32:47]
	s_waitcnt lgkmcnt(4)
	v_mfma_f32_32x32x16_bf16 v[48:63], v[126:129], v[78:81], v[48:63]
	s_waitcnt lgkmcnt(3)
	v_mfma_f32_32x32x16_bf16 v[48:63], v[130:133], v[82:85], v[48:63]
	s_waitcnt lgkmcnt(2)
	v_mfma_f32_32x32x16_bf16 v[48:63], v[140:143], v[90:93], v[48:63]
	s_waitcnt lgkmcnt(1)
	v_mfma_f32_32x32x16_bf16 v[48:63], v[144:147], v[94:97], v[48:63]
	s_waitcnt lgkmcnt(0)
	v_mfma_f32_32x32x16_bf16 v[48:63], v[148:151], v[98:101], v[48:63]
	v_add_u32_e32 v172, v119, v115
	ds_read_b64_tr_b16 v[156:157], v172 offset:13312
	ds_read_b64_tr_b16 v[158:159], v172 offset:14848
	ds_read_b64_tr_b16 v[160:161], v172 offset:16384
	ds_read_b64_tr_b16 v[162:163], v172 offset:17920
	ds_read_b64_tr_b16 v[164:165], v172 offset:13376
	ds_read_b64_tr_b16 v[166:167], v172 offset:14912
	ds_read_b64_tr_b16 v[168:169], v172 offset:16448
	ds_read_b64_tr_b16 v[170:171], v172 offset:17984
	ds_read_b128 v[202:205], v120 offset:6656
	ds_read_b128 v[206:209], v120 offset:6688
	ds_read_b128 v[210:213], v120 offset:6720
	ds_read_b128 v[214:217], v120 offset:6752
	ds_read_b128 v[218:221], v120 offset:6784
	ds_read_b128 v[222:225], v120 offset:6816
	s_setprio 0
	s_add_i32 s30, s29, 0x5f
	s_cmp_le_i32 s30, s22
	s_cbranch_scc1 .LBB0_1105
	v_add_u32_e32 v121, s29, v105
	v_add_u32_e32 v122, 64, v121
	v_cmp_lt_i32_e32 vcc, v122, v139
	s_nop 4
	v_cndmask_b32_e32 v49, v239, v49, vcc
	v_cmp_le_i32_e32 vcc, v122, v139
	v_add_u32_e32 v122, 0x42, v121
	s_nop 0
	v_cndmask_b32_e32 v48, v239, v48, vcc
	v_cmp_le_i32_e32 vcc, v122, v139
	v_add_u32_e32 v122, 0x43, v121
	s_nop 0
	v_cndmask_b32_e32 v50, v239, v50, vcc
	v_cmp_le_i32_e32 vcc, v122, v139
	v_add_u32_e32 v122, 0x48, v121
	s_nop 0
	v_cndmask_b32_e32 v51, v239, v51, vcc
	v_cmp_le_i32_e32 vcc, v122, v139
	v_add_u32_e32 v122, 0x49, v121
	s_nop 0
	v_cndmask_b32_e32 v52, v239, v52, vcc
	v_cmp_le_i32_e32 vcc, v122, v139
	v_add_u32_e32 v122, 0x4a, v121
	s_nop 0
	v_cndmask_b32_e32 v53, v239, v53, vcc
	v_cmp_le_i32_e32 vcc, v122, v139
	v_add_u32_e32 v122, 0x4b, v121
	s_nop 0
	v_cndmask_b32_e32 v54, v239, v54, vcc
	v_cmp_le_i32_e32 vcc, v122, v139
	v_add_u32_e32 v122, 0x50, v121
	s_nop 0
	v_cndmask_b32_e32 v55, v239, v55, vcc
	v_cmp_le_i32_e32 vcc, v122, v139
	v_add_u32_e32 v122, 0x51, v121
	s_nop 0
	v_cndmask_b32_e32 v56, v239, v56, vcc
	v_cmp_le_i32_e32 vcc, v122, v139
	v_add_u32_e32 v122, 0x52, v121
	s_nop 0
	v_cndmask_b32_e32 v57, v239, v57, vcc
	v_cmp_le_i32_e32 vcc, v122, v139
	v_add_u32_e32 v122, 0x53, v121
	s_nop 0
	v_cndmask_b32_e32 v58, v239, v58, vcc
	v_cmp_le_i32_e32 vcc, v122, v139
	v_add_u32_e32 v122, 0x58, v121
	s_nop 0
	v_cndmask_b32_e32 v59, v239, v59, vcc
	v_cmp_le_i32_e32 vcc, v122, v139
	v_add_u32_e32 v122, 0x59, v121
	s_nop 0
	v_cndmask_b32_e32 v60, v239, v60, vcc
	v_cmp_le_i32_e32 vcc, v122, v139
	v_add_u32_e32 v122, 0x5a, v121
	v_add_u32_e32 v121, 0x5b, v121
	v_cndmask_b32_e32 v61, v239, v61, vcc
	v_cmp_le_i32_e32 vcc, v122, v139
	s_nop 1
	v_cndmask_b32_e32 v62, v239, v62, vcc
	v_cmp_le_i32_e32 vcc, v121, v139
	s_nop 1
	v_cndmask_b32_e32 v63, v239, v63, vcc

; __device__ __forceinline__ unsigned cvt_pk_bf16(float lo, float hi) { const f32x2c_ v = {lo, hi}; const bf16x2c_ b = __builtin_convertvector(v, bf16x2c_); return __builtin_bit_cast(unsigned, b); }
; #define LAS __attribute__((address_space(3)))
; #define MFMA32(a, b, c) __builtin_amdgcn_mfma_f32_32x32x16_bf16(a, b, c, 0, 0, 0)
; __device__ __forceinline__ void attn_unit(int bh, int qb, const bf16_t* QKV, const bf16_t* KF, const float* cstab, const float* qg, bf16_t* MIX, LAS unsigned char* lds) {
;     ...
;             float ps = 0.f;
; #pragma unroll
;             for (int r = 0; r < 16; ++r) { p[r] = __builtin_amdgcn_exp2f(p[r]); ps += p[r]; }
;             lrun += ps;
;             u32x4 w0, w1;
; #pragma unroll
;             for (int k = 0; k < 4; ++k) { w0[k] = cvt_pk_bf16(p[2 * k], p[2 * k + 1]); w1[k] = cvt_pk_bf16(p[8 + 2 * k], p[8 + 2 * k + 1]); }
;             const bf16x8 pb0 = __builtin_bit_cast(bf16x8, w0), pb1 = __builtin_bit_cast(bf16x8, w1);
;             const LAS unsigned char* vp = buf + vtb + (32 * kb) * VROW;
; #pragma unroll
;             for (int db = 0; db < 2; ++db) {
;                 const v4i16_t a0 = __builtin_amdgcn_ds_read_tr16_b64_v4i16((LAS v4i16_t*)(vp + db * 64));
;                 const v4i16_t a1 = __builtin_amdgcn_ds_read_tr16_b64_v4i16((LAS v4i16_t*)(vp + db * 64 + 8 * VROW));
;                 const v4i16_t c0 = __builtin_amdgcn_ds_read_tr16_b64_v4i16((LAS v4i16_t*)(vp + db * 64 + 16 * VROW));
;                 const v4i16_t c1 = __builtin_amdgcn_ds_read_tr16_b64_v4i16((LAS v4i16_t*)(vp + db * 64 + 24 * VROW));
;                 const bf16x8 va = {a0[0], a0[1], a0[2], a0[3], a1[0], a1[1], a1[2], a1[3]}, vc = {c0[0], c0[1], c0[2], c0[3], c1[0], c1[1], c1[2], c1[3]};
;                 __builtin_amdgcn_s_setprio(1);
;                 if (db == 0) { o0 = MFMA32(va, pb0, o0); o0 = MFMA32(vc, pb1, o0); }
;                 else { o1 = MFMA32(va, pb0, o1); o1 = MFMA32(vc, pb1, o1); }
;                 __builtin_amdgcn_s_setprio(0);
;             }
.LBB0_1107:
	v_exp_f32_e32 v48, v48
	v_exp_f32_e32 v49, v49
	v_exp_f32_e32 v50, v50
	v_exp_f32_e32 v51, v51
	v_exp_f32_e32 v122, v52
	v_add_f32_e32 v121, v49, v48
	v_add_f32_e32 v121, v50, v121
	v_add_f32_e32 v121, v51, v121
	v_add_f32_e32 v52, v122, v121
	v_exp_f32_e32 v121, v53
	v_exp_f32_e32 v123, v54
	v_exp_f32_e32 v55, v55
	v_exp_f32_e32 v53, v56
	v_add_f32_e32 v52, v121, v52
	v_exp_f32_e32 v54, v57
	v_add_f32_e32 v52, v123, v52
	v_exp_f32_e32 v56, v58
	v_add_f32_e32 v52, v55, v52
	v_exp_f32_e32 v57, v59
	v_add_f32_e32 v52, v53, v52
	v_exp_f32_e32 v58, v60
	v_add_f32_e32 v52, v54, v52
	v_exp_f32_e32 v59, v61
	v_add_f32_e32 v52, v56, v52
	v_exp_f32_e32 v60, v62
	v_add_f32_e32 v52, v57, v52
	v_exp_f32_e32 v61, v63
	v_add_f32_e32 v52, v58, v52
	v_add_f32_e32 v52, v59, v52
	v_add_f32_e32 v52, v60, v52
	v_cvt_pk_bf16_f32 v48, v48, v49
	v_cvt_pk_bf16_f32 v49, v50, v51
	v_cvt_pk_bf16_f32 v50, v122, v121
	v_add_f32_e32 v124, v61, v52
	v_cvt_pk_bf16_f32 v52, v53, v54
	v_cvt_pk_bf16_f32 v53, v56, v57
	v_cvt_pk_bf16_f32 v54, v58, v59
	v_cvt_pk_bf16_f32 v51, v123, v55
	v_cvt_pk_bf16_f32 v55, v60, v61
	s_setprio 1
	s_waitcnt lgkmcnt(12)
	v_mfma_f32_32x32x16_bf16 v[0:15], v[156:159], v[48:51], v[0:15]
	s_waitcnt lgkmcnt(10)
	v_mfma_f32_32x32x16_bf16 v[0:15], v[160:163], v[52:55], v[0:15]
	s_setprio 0
	s_setprio 1
	s_waitcnt lgkmcnt(8)
	v_mfma_f32_32x32x16_bf16 v[16:31], v[164:167], v[48:51], v[16:31]
	s_waitcnt lgkmcnt(6)
	v_mfma_f32_32x32x16_bf16 v[16:31], v[168:171], v[52:55], v[16:31]
	s_setprio 0
	v_add_f32_e32 v107, v107, v124
	s_add_i32 s30, s29, 0x60
	s_cmp_gt_i32 s30, s18
	s_cbranch_scc0 .LBB0_1110

; #define LAS __attribute__((address_space(3)))
; #define MFMA32(a, b, c) __builtin_amdgcn_mfma_f32_32x32x16_bf16(a, b, c, 0, 0, 0)
; __device__ __forceinline__ void attn_unit(int bh, int qb, const bf16_t* QKV, const bf16_t* KF, const float* cstab, const float* qg, bf16_t* MIX, LAS unsigned char* lds) {
;     ...
;             if (key0 > qw + 31) continue;
;             const LAS unsigned char* kp = buf + (32 * kb + r32) * KROW + 16 * hi;
;             f32x16 p = negm;
;             bf16x8 kfr[6];
; #pragma unroll
;             for (int d0 = 0; d0 < 6; ++d0) kfr[d0] = *(const LAS bf16x8*)(kp + 32 * d0);
;             __builtin_amdgcn_s_setprio(1);
; #pragma unroll
;             for (int d0 = 0; d0 < 6; ++d0) p = MFMA32(kfr[d0], qf[d0], p);
;             __builtin_amdgcn_s_setprio(0);
;             if (key0 + 31 > qw) {
; #pragma unroll
;                 for (int r = 0; r < 16; ++r) { const int key = key0 + (r & 3) + 8 * (r >> 2) + 4 * hi; if (key > q) p[r] = -1e30f; }
;     ...
;             const LAS unsigned char* vp = buf + vtb + (32 * kb) * VROW;
; #pragma unroll
;             for (int db = 0; db < 2; ++db) {
;                 const v4i16_t a0 = __builtin_amdgcn_ds_read_tr16_b64_v4i16((LAS v4i16_t*)(vp + db * 64));
;                 const v4i16_t a1 = __builtin_amdgcn_ds_read_tr16_b64_v4i16((LAS v4i16_t*)(vp + db * 64 + 8 * VROW));
;                 const v4i16_t c0 = __builtin_amdgcn_ds_read_tr16_b64_v4i16((LAS v4i16_t*)(vp + db * 64 + 16 * VROW));
;                 const v4i16_t c1 = __builtin_amdgcn_ds_read_tr16_b64_v4i16((LAS v4i16_t*)(vp + db * 64 + 24 * VROW));
.LBB0_1110:
	s_setprio 1
	s_waitcnt lgkmcnt(5)
	v_mfma_f32_32x32x16_bf16 v[48:63], v[202:205], v[74:77], v[32:47]
	s_waitcnt lgkmcnt(4)
	v_mfma_f32_32x32x16_bf16 v[48:63], v[206:209], v[78:81], v[48:63]
	s_waitcnt lgkmcnt(3)
	v_mfma_f32_32x32x16_bf16 v[48:63], v[210:213], v[82:85], v[48:63]
	s_waitcnt lgkmcnt(2)
	v_mfma_f32_32x32x16_bf16 v[48:63], v[214:217], v[90:93], v[48:63]
	s_waitcnt lgkmcnt(1)
	v_mfma_f32_32x32x16_bf16 v[48:63], v[218:221], v[94:97], v[48:63]
	s_waitcnt lgkmcnt(0)
	v_mfma_f32_32x32x16_bf16 v[48:63], v[222:225], v[98:101], v[48:63]
	v_add_u32_e32 v172, v119, v115
	ds_read_b64_tr_b16 v[156:157], v172 offset:19456
	ds_read_b64_tr_b16 v[158:159], v172 offset:20992
	ds_read_b64_tr_b16 v[160:161], v172 offset:22528
	ds_read_b64_tr_b16 v[162:163], v172 offset:24064
	ds_read_b64_tr_b16 v[164:165], v172 offset:19520
	ds_read_b64_tr_b16 v[166:167], v172 offset:21056
	ds_read_b64_tr_b16 v[168:169], v172 offset:22592
	ds_read_b64_tr_b16 v[170:171], v172 offset:24128
	s_setprio 0
	s_add_i32 s30, s29, 0x7f
	s_cmp_le_i32 s30, s22
	s_cbranch_scc1 .LBB0_1112
	v_add_u32_e32 v120, s29, v105
	v_add_u32_e32 v121, 0x60, v120
	v_cmp_lt_i32_e32 vcc, v121, v139
	s_nop 4
	v_cndmask_b32_e32 v49, v239, v49, vcc
	v_cmp_le_i32_e32 vcc, v121, v139
	v_add_u32_e32 v121, 0x62, v120
	s_nop 0
	v_cndmask_b32_e32 v48, v239, v48, vcc
	v_cmp_le_i32_e32 vcc, v121, v139
	v_add_u32_e32 v121, 0x63, v120
	s_nop 0
	v_cndmask_b32_e32 v50, v239, v50, vcc
	v_cmp_le_i32_e32 vcc, v121, v139
	v_add_u32_e32 v121, 0x68, v120
	s_nop 0
	v_cndmask_b32_e32 v51, v239, v51, vcc
	v_cmp_le_i32_e32 vcc, v121, v139
	v_add_u32_e32 v121, 0x69, v120
	s_nop 0
	v_cndmask_b32_e32 v52, v239, v52, vcc
	v_cmp_le_i32_e32 vcc, v121, v139
	v_add_u32_e32 v121, 0x6a, v120
	s_nop 0
	v_cndmask_b32_e32 v53, v239, v53, vcc
	v_cmp_le_i32_e32 vcc, v121, v139
	v_add_u32_e32 v121, 0x6b, v120
	s_nop 0
	v_cndmask_b32_e32 v54, v239, v54, vcc
	v_cmp_le_i32_e32 vcc, v121, v139
	v_add_u32_e32 v121, 0x70, v120
	s_nop 0
	v_cndmask_b32_e32 v55, v239, v55, vcc
	v_cmp_le_i32_e32 vcc, v121, v139
	v_add_u32_e32 v121, 0x71, v120
	s_nop 0
	v_cndmask_b32_e32 v56, v239, v56, vcc
	v_cmp_le_i32_e32 vcc, v121, v139
	v_add_u32_e32 v121, 0x72, v120
	s_nop 0
	v_cndmask_b32_e32 v57, v239, v57, vcc
	v_cmp_le_i32_e32 vcc, v121, v139
	v_add_u32_e32 v121, 0x73, v120
	s_nop 0
	v_cndmask_b32_e32 v58, v239, v58, vcc
	v_cmp_le_i32_e32 vcc, v121, v139
	v_add_u32_e32 v121, 0x78, v120
	s_nop 0
	v_cndmask_b32_e32 v59, v239, v59, vcc
	v_cmp_le_i32_e32 vcc, v121, v139
	v_add_u32_e32 v121, 0x79, v120
	s_nop 0
	v_cndmask_b32_e32 v60, v239, v60, vcc
	v_cmp_le_i32_e32 vcc, v121, v139
	v_add_u32_e32 v121, 0x7a, v120
	v_add_u32_e32 v120, 0x7b, v120
	v_cndmask_b32_e32 v61, v239, v61, vcc
	v_cmp_le_i32_e32 vcc, v121, v139
	s_nop 1
	v_cndmask_b32_e32 v62, v239, v62, vcc
	v_cmp_le_i32_e32 vcc, v120, v139
	s_nop 1
	v_cndmask_b32_e32 v63, v239, v63, vcc
